# first GEMM phase without the baseline's start-time stagger (stagger ticks 350 -> 0)
# speedup vs baseline: 1.0034x; 1.0034x over previous
.LBB0_80:
	s_or_b64 exec, exec, s[28:29]
	s_bfe_u32 s6, s2, 0x20003
	s_cmp_lg_u32 s6, 0
	s_mov_b32 s39, 0
	s_waitcnt lgkmcnt(0)
	s_barrier
	s_cbranch_scc0 .LBB0_84
	s_memrealtime s[28:29]
	s_memrealtime s[16:17]
	s_mul_i32 s38, s6, 0
	v_mov_b64_e32 v[0:1], s[38:39]
	s_waitcnt lgkmcnt(0)
	s_sub_u32 s6, s16, s28
	s_subb_u32 s7, s17, s29
	v_cmp_ge_u64_e32 vcc, s[6:7], v[0:1]
	s_cbranch_vccnz .LBB0_84
	v_mov_b64_e32 v[0:1], s[38:39]
